# P5 g/beta elementwise loop: loop-invariant dt_bias/A_log loads hoisted out, next iteration's a/b loads prefetched under the current iteration's softplus/sigmoid math
# speedup vs baseline: 1.0007x; 1.0007x over previous
.LBB0_596:
	v_readlane_b32 s0, v251, 42
	s_lshl_b32 s13, s0, 9
	v_readlane_b32 s0, v252, 2
	v_readlane_b32 s1, v252, 3
	v_add_u32_e32 v2, s13, v58
	s_mov_b32 s1, 0x80000
	s_lshl_b32 s0, s0, 9
	v_cmp_gt_i32_e32 vcc, s1, v2
	s_and_saveexec_b64 s[4:5], vcc
	s_cbranch_execz .LBB0_599
	v_and_b32_e32 v3, 31, v58
	v_lshlrev_b32_e32 v8, 2, v3
	v_mov_b32_e32 v9, 0
	v_lshl_add_u64 v[4:5], s[94:95], 0, v[8:9]
	s_mov_b64 s[6:7], 0x400000
	v_readlane_b32 s16, v252, 12
	v_ashrrev_i32_e32 v3, 31, v2
	v_lshl_add_u64 v[4:5], v[4:5], 0, s[6:7]
	v_readlane_b32 s17, v252, 13
	v_readlane_b32 s18, v252, 14
	v_readlane_b32 s19, v252, 15
	v_lshl_add_u64 v[10:11], v[2:3], 2, s[94:95]
	s_mov_b64 s[6:7], 0x800000
	s_ashr_i32 s1, s0, 31
	v_lshl_add_u64 v[6:7], s[18:19], 0, v[8:9]
	v_lshl_add_u64 v[8:9], s[16:17], 0, v[8:9]
	v_lshl_add_u64 v[10:11], v[10:11], 0, s[6:7]
	s_lshl_b64 s[6:7], s[0:1], 2
	s_mov_b64 s[8:9], 0
	s_mov_b32 s1, 0xbfb8aa3b
	s_mov_b32 s14, 0x42ce8ed0
	s_mov_b32 s15, 0xc2b17218
	v_mov_b32_e32 v3, 0x7f800000
	v_mov_b32_e32 v12, 0x3ecc95a3
	v_readlane_b32 s20, v252, 16
	v_readlane_b32 s21, v252, 17
	v_readlane_b32 s22, v252, 18
	v_readlane_b32 s23, v252, 19
	v_readlane_b32 s24, v252, 20
	v_readlane_b32 s25, v252, 21
	v_readlane_b32 s26, v252, 22
	v_readlane_b32 s27, v252, 23
	v_readlane_b32 s28, v252, 24
	v_readlane_b32 s29, v252, 25
	v_readlane_b32 s30, v252, 26
	v_readlane_b32 s31, v252, 27
	v_ashrrev_i32_e32 v14, 5, v2
	v_ashrrev_i32_e32 v15, 31, v14
	v_lshlrev_b64 v[14:15], 8, v[14:15]
	v_lshl_add_u64 v[14:15], v[4:5], 0, v[14:15]
	global_load_dword v29, v[14:15], off
	global_load_dword v30, v[14:15], off offset:128
	global_load_dword v27, v[6:7], off
	global_load_dword v28, v[8:9], off
.LBB0_598:
	v_add_u32_e32 v2, s0, v2
	s_mov_b32 s16, 0xb2a5705f
	v_ashrrev_i32_e32 v14, 5, v2
	v_ashrrev_i32_e32 v15, 31, v14
	v_lshlrev_b64 v[14:15], 8, v[14:15]
	v_lshl_add_u64 v[14:15], v[4:5], 0, v[14:15]
	s_waitcnt vmcnt(0)
	v_mov_b32_e32 v16, v29
	v_mov_b32_e32 v13, v30
	global_load_dword v29, v[14:15], off
	global_load_dword v30, v[14:15], off offset:128
	v_add_f32_e32 v14, v16, v27
	v_mul_f32_e64 v15, |v14|, s1
	v_fma_f32 v17, |v14|, s1, -v15
	v_rndne_f32_e32 v18, v15
	v_fma_f32 v17, |v14|, s16, v17
	v_sub_f32_e32 v15, v15, v18
	v_add_f32_e32 v15, v15, v17
	v_exp_f32_e32 v15, v15
	v_cvt_i32_f32_e32 v17, v18
	v_cmp_ngt_f32_e64 vcc, |v14|, s14
	v_max_f32_e32 v16, 0, v14
	s_mov_b32 s16, 0x3f2aaaab
	v_ldexp_f32 v15, v15, v17
	v_cndmask_b32_e32 v15, 0, v15, vcc
	v_cmp_nlt_f32_e64 vcc, |v14|, s15
	s_nop 1
	v_cndmask_b32_e32 v17, v3, v15, vcc
	v_add_f32_e32 v18, 1.0, v17
	v_add_f32_e32 v14, -1.0, v18
	v_sub_f32_e32 v15, v14, v18
	v_add_f32_e32 v15, 1.0, v15
	v_sub_f32_e32 v14, v17, v14
	v_add_f32_e32 v19, v14, v15
	v_frexp_mant_f32_e32 v14, v18
	v_cmp_gt_f32_e32 vcc, s16, v14
	v_cvt_f64_f32_e32 v[14:15], v18
	v_frexp_exp_i32_f64_e32 v14, v[14:15]
	v_subbrev_co_u32_e32 v14, vcc, 0, v14, vcc
	v_sub_u32_e32 v15, 0, v14
	v_ldexp_f32 v18, v18, v15
	v_ldexp_f32 v15, v19, v15
	v_add_f32_e32 v19, -1.0, v18
	v_add_f32_e32 v20, 1.0, v19
	v_sub_f32_e32 v20, v18, v20
	v_add_f32_e32 v20, v15, v20
	v_add_f32_e32 v21, v19, v20
	v_sub_f32_e32 v19, v19, v21
	v_add_f32_e32 v19, v20, v19
	v_add_f32_e32 v20, 1.0, v18
	v_add_f32_e32 v22, -1.0, v20
	v_sub_f32_e32 v18, v18, v22
	v_add_f32_e32 v15, v15, v18
	v_add_f32_e32 v18, v20, v15
	v_sub_f32_e32 v20, v20, v18
	v_add_f32_e32 v15, v15, v20
	v_rcp_f32_e32 v20, v18
	v_cvt_f32_i32_e32 v14, v14
	s_mov_b32 s16, 0x3f317218
	v_mul_f32_e32 v22, v21, v20
	v_mul_f32_e32 v23, v18, v22
	v_fma_f32 v24, v22, v18, -v23
	v_fmac_f32_e32 v24, v22, v15
	v_add_f32_e32 v25, v23, v24
	v_sub_f32_e32 v26, v21, v25
	v_sub_f32_e32 v21, v21, v26
	v_sub_f32_e32 v23, v25, v23
	v_sub_f32_e32 v21, v21, v25
	v_add_f32_e32 v19, v19, v21
	v_sub_f32_e32 v21, v23, v24
	v_add_f32_e32 v19, v21, v19
	v_add_f32_e32 v21, v26, v19
	v_mul_f32_e32 v23, v20, v21
	v_mul_f32_e32 v24, v18, v23
	v_fma_f32 v18, v23, v18, -v24
	v_fmac_f32_e32 v18, v23, v15
	v_sub_f32_e32 v15, v26, v21
	v_add_f32_e32 v15, v19, v15
	v_add_f32_e32 v19, v24, v18
	v_sub_f32_e32 v25, v21, v19
	v_sub_f32_e32 v21, v21, v25
	v_sub_f32_e32 v24, v19, v24
	v_sub_f32_e32 v19, v21, v19
	v_add_f32_e32 v15, v15, v19
	v_sub_f32_e32 v18, v24, v18
	v_add_f32_e32 v15, v18, v15
	v_add_f32_e32 v18, v22, v23
	v_add_f32_e32 v15, v25, v15
	v_sub_f32_e32 v19, v18, v22
	v_mul_f32_e32 v15, v20, v15
	v_sub_f32_e32 v19, v23, v19
	v_add_f32_e32 v15, v19, v15
	v_mul_f32_e32 v22, 0x3f317218, v14
	v_add_f32_e32 v19, v18, v15
	v_fma_f32 v23, v14, s16, -v22
	v_mul_f32_e32 v20, v19, v19
	v_fmac_f32_e32 v23, 0xb102e308, v14
	v_sub_f32_e32 v14, v19, v18
	v_fmamk_f32 v21, v20, 0x3e9b6dac, v12
	v_sub_f32_e32 v14, v15, v14
	v_add_f32_e32 v15, v22, v23
	v_fmaak_f32 v21, v20, v21, 0x3f2aaada
	v_sub_f32_e32 v18, v15, v22
	v_ldexp_f32 v22, v19, 1
	v_mul_f32_e32 v19, v19, v20
	v_mul_f32_e32 v19, v19, v21
	v_add_f32_e32 v20, v22, v19
	v_sub_f32_e32 v21, v20, v22
	v_ldexp_f32 v14, v14, 1
	v_sub_f32_e32 v19, v19, v21
	v_add_f32_e32 v14, v14, v19
	v_add_f32_e32 v19, v20, v14
	v_sub_f32_e32 v20, v19, v20
	v_sub_f32_e32 v14, v14, v20
	v_add_f32_e32 v20, v15, v19
	v_sub_f32_e32 v21, v20, v15
	v_sub_f32_e32 v22, v20, v21
	v_sub_f32_e32 v18, v23, v18
	v_sub_f32_e32 v15, v15, v22
	v_sub_f32_e32 v19, v19, v21
	v_add_f32_e32 v15, v19, v15
	v_add_f32_e32 v19, v18, v14
	v_sub_f32_e32 v21, v19, v18
	v_sub_f32_e32 v22, v19, v21
	v_sub_f32_e32 v18, v18, v22
	v_sub_f32_e32 v14, v14, v21
	v_add_f32_e32 v15, v19, v15
	v_add_f32_e32 v14, v14, v18
	v_add_f32_e32 v18, v20, v15
	v_sub_f32_e32 v19, v18, v20
	v_sub_f32_e32 v15, v15, v19
	v_add_f32_e32 v14, v14, v15
	v_mov_b32_e32 v15, v28
	s_mov_b32 s16, 0x7f800000
	v_add_f32_e32 v14, v18, v14
	v_cmp_neq_f32_e32 vcc, s16, v17
	s_mov_b32 s16, 0x33800000
	s_nop 0
	v_cndmask_b32_e32 v14, v3, v14, vcc
	v_cmp_lt_f32_e64 vcc, |v17|, s16
	s_mov_b32 s16, 0x3fb8aa3b
	s_nop 0
	v_cndmask_b32_e32 v14, v14, v17, vcc
	v_add_f32_e32 v14, v16, v14
	s_nop 0
	v_mul_f32_e32 v16, 0x3fb8aa3b, v15
	v_rndne_f32_e32 v17, v16
	v_sub_f32_e32 v18, v16, v17
	v_fma_f32 v16, v15, s16, -v16
	v_fmac_f32_e32 v16, 0x32a5705f, v15
	v_add_f32_e32 v16, v18, v16
	v_exp_f32_e32 v16, v16
	v_cvt_i32_f32_e32 v17, v17
	s_mov_b32 s16, 0xc2ce8ed0
	v_cmp_ngt_f32_e32 vcc, s16, v15
	s_mov_b32 s16, 0x42b17218
	v_ldexp_f32 v16, v16, v17
	v_cndmask_b32_e32 v16, 0, v16, vcc
	v_cmp_nlt_f32_e32 vcc, s16, v15
	s_nop 1
	v_cndmask_b32_e32 v15, v3, v16, vcc
	v_mul_f32_e64 v14, v14, -v15
	global_store_dword v[10:11], v14, off
	v_mul_f32_e32 v14, 0xbfb8aa3b, v13
	v_fma_f32 v15, v13, s1, -v14
	v_rndne_f32_e32 v16, v14
	v_fmac_f32_e32 v15, 0xb2a5705f, v13
	v_sub_f32_e32 v14, v14, v16
	v_add_f32_e32 v14, v14, v15
	v_exp_f32_e32 v14, v14
	v_cvt_i32_f32_e32 v15, v16
	v_cmp_nlt_f32_e32 vcc, s14, v13
	v_ldexp_f32 v14, v14, v15
	s_nop 0
	v_cndmask_b32_e32 v14, 0, v14, vcc
	v_cmp_ngt_f32_e32 vcc, s15, v13
	s_nop 1
	v_cndmask_b32_e32 v13, v3, v14, vcc
	v_add_f32_e32 v13, 1.0, v13
	v_div_scale_f32 v14, s[16:17], v13, v13, 1.0
	v_rcp_f32_e32 v15, v14
	s_mov_b32 s16, 0x7ffff
	v_fma_f32 v16, -v14, v15, 1.0
	v_fmac_f32_e32 v15, v16, v15
	v_div_scale_f32 v16, vcc, 1.0, v13, 1.0
	v_mul_f32_e32 v17, v16, v15
	v_fma_f32 v18, -v14, v17, v16
	v_fmac_f32_e32 v17, v18, v15
	v_fma_f32 v14, -v14, v17, v16
	v_div_fmas_f32 v14, v14, v15, v17
	v_div_fixup_f32 v13, v14, v13, 1.0
	v_add_co_u32_e32 v14, vcc, 0x200000, v10
	s_nop 1
	v_addc_co_u32_e32 v15, vcc, 0, v11, vcc
	v_cmp_lt_i32_e32 vcc, s16, v2
	v_lshl_add_u64 v[10:11], v[10:11], 0, s[6:7]
	s_or_b64 s[8:9], vcc, s[8:9]
	global_store_dword v[14:15], v13, off
	s_andn2_b64 exec, exec, s[8:9]
	s_cbranch_execnz .LBB0_598
